# comb17 + non-temporal hint on the 32 final f32 output stores
# baseline (speedup 1.0000x reference)
;     __device__ __forceinline__ void operator()(f32x4 (&acc)[2][2][4][2], const Unit& u, int wr, int wc, int fr, int fq) const {
;     ...
;         asm volatile("s_waitcnt vmcnt(0) lgkmcnt(0)" ::: "memory"); __builtin_amdgcn_s_barrier(); asm volatile("" ::: "memory");
; #pragma unroll
;         for (int ai = 0; ai < 2; ++ai)
; #pragma unroll
;             for (int m = 0; m < 4; ++m) { const int rl = ai * HALF + wr * 64 + m * 16 + fr; const float rstd = R[rl]; float* orow = out + (size_t)(u.pm * BM + rl) * D + col0;
; #pragma unroll
;                 for (int bj = 0; bj < 2; ++bj) { const f32x4 g0 = *(const f32x4*)(gain + col0 + bj * HALF), g1 = *(const f32x4*)(gain + col0 + bj * HALF + 4);
;                     *(f32x4*)(orow + bj * HALF) = acc[ai][bj][m][0] * rstd * g0; *(f32x4*)(orow + bj * HALF + 4) = acc[ai][bj][m][1] * rstd * g1; } }
.LBB0_1314:
	s_or_b64 exec, exec, s[54:55]
	v_lshlrev_b64 v[158:159], 2, v[148:149]
	s_waitcnt vmcnt(0) lgkmcnt(0)
	s_barrier
	v_lshl_add_u64 v[148:149], s[22:23], 0, v[158:159]
	global_load_dwordx4 v[4:7], v[148:149], off
	s_waitcnt lgkmcnt(0)
	global_load_dwordx4 v[0:3], v[148:149], off offset:16
	v_lshlrev_b64 v[146:147], 13, v[146:147]
	v_lshl_add_u64 v[146:147], s[12:13], 0, v[146:147]
	ds_read_b32 v136, v178
	ds_read_b32 v160, v179
	ds_read_b32 v162, v180
	ds_read_b32 v164, v181
	ds_read_b32 v166, v182
	ds_read_b32 v168, v183
	ds_read_b32 v172, v184
	ds_read_b32 v170, v185
	s_waitcnt lgkmcnt(7)
	v_pk_mul_f32 v[126:127], v[126:127], v[136:137] op_sel_hi:[1,0]
	v_pk_mul_f32 v[124:125], v[124:125], v[136:137] op_sel_hi:[1,0]
	v_lshl_add_u64 v[146:147], v[146:147], 0, v[158:159]
	v_pk_mul_f32 v[122:123], v[122:123], v[136:137] op_sel_hi:[1,0]
	v_pk_mul_f32 v[120:121], v[120:121], v[136:137] op_sel_hi:[1,0]
	v_pk_mul_f32 v[118:119], v[118:119], v[136:137] op_sel_hi:[1,0]
	v_pk_mul_f32 v[116:117], v[116:117], v[136:137] op_sel_hi:[1,0]
	v_pk_mul_f32 v[114:115], v[114:115], v[136:137] op_sel_hi:[1,0]
	v_pk_mul_f32 v[112:113], v[112:113], v[136:137] op_sel_hi:[1,0]
	s_waitcnt lgkmcnt(6)
	v_pk_mul_f32 v[110:111], v[110:111], v[160:161] op_sel_hi:[1,0]
	v_pk_mul_f32 v[108:109], v[108:109], v[160:161] op_sel_hi:[1,0]
	v_pk_mul_f32 v[106:107], v[106:107], v[160:161] op_sel_hi:[1,0]
	v_pk_mul_f32 v[104:105], v[104:105], v[160:161] op_sel_hi:[1,0]
	v_pk_mul_f32 v[102:103], v[102:103], v[160:161] op_sel_hi:[1,0]
	v_pk_mul_f32 v[100:101], v[100:101], v[160:161] op_sel_hi:[1,0]
	v_pk_mul_f32 v[98:99], v[98:99], v[160:161] op_sel_hi:[1,0]
	v_pk_mul_f32 v[96:97], v[96:97], v[160:161] op_sel_hi:[1,0]
	s_waitcnt lgkmcnt(5)
	v_pk_mul_f32 v[94:95], v[94:95], v[162:163] op_sel_hi:[1,0]
	v_pk_mul_f32 v[92:93], v[92:93], v[162:163] op_sel_hi:[1,0]
	v_pk_mul_f32 v[90:91], v[90:91], v[162:163] op_sel_hi:[1,0]
	v_pk_mul_f32 v[88:89], v[88:89], v[162:163] op_sel_hi:[1,0]
	v_pk_mul_f32 v[86:87], v[86:87], v[162:163] op_sel_hi:[1,0]
	v_pk_mul_f32 v[84:85], v[84:85], v[162:163] op_sel_hi:[1,0]
	v_pk_mul_f32 v[82:83], v[82:83], v[162:163] op_sel_hi:[1,0]
	v_pk_mul_f32 v[80:81], v[80:81], v[162:163] op_sel_hi:[1,0]
	s_waitcnt lgkmcnt(4)
	v_pk_mul_f32 v[78:79], v[78:79], v[164:165] op_sel_hi:[1,0]
	v_pk_mul_f32 v[76:77], v[76:77], v[164:165] op_sel_hi:[1,0]
	v_pk_mul_f32 v[74:75], v[74:75], v[164:165] op_sel_hi:[1,0]
	v_pk_mul_f32 v[72:73], v[72:73], v[164:165] op_sel_hi:[1,0]
	v_pk_mul_f32 v[70:71], v[70:71], v[164:165] op_sel_hi:[1,0]
	v_pk_mul_f32 v[68:69], v[68:69], v[164:165] op_sel_hi:[1,0]
	v_pk_mul_f32 v[66:67], v[66:67], v[164:165] op_sel_hi:[1,0]
	v_pk_mul_f32 v[64:65], v[64:65], v[164:165] op_sel_hi:[1,0]
	s_waitcnt lgkmcnt(3)
	v_pk_mul_f32 v[62:63], v[62:63], v[166:167] op_sel_hi:[1,0]
	v_pk_mul_f32 v[60:61], v[60:61], v[166:167] op_sel_hi:[1,0]
	v_pk_mul_f32 v[58:59], v[58:59], v[166:167] op_sel_hi:[1,0]
	v_pk_mul_f32 v[56:57], v[56:57], v[166:167] op_sel_hi:[1,0]
	v_pk_mul_f32 v[54:55], v[54:55], v[166:167] op_sel_hi:[1,0]
	v_pk_mul_f32 v[52:53], v[52:53], v[166:167] op_sel_hi:[1,0]
	v_pk_mul_f32 v[50:51], v[50:51], v[166:167] op_sel_hi:[1,0]
	v_pk_mul_f32 v[48:49], v[48:49], v[166:167] op_sel_hi:[1,0]
	s_waitcnt lgkmcnt(2)
	v_pk_mul_f32 v[46:47], v[46:47], v[168:169] op_sel_hi:[1,0]
	v_pk_mul_f32 v[44:45], v[44:45], v[168:169] op_sel_hi:[1,0]
	v_pk_mul_f32 v[42:43], v[42:43], v[168:169] op_sel_hi:[1,0]
	v_pk_mul_f32 v[40:41], v[40:41], v[168:169] op_sel_hi:[1,0]
	v_pk_mul_f32 v[38:39], v[38:39], v[168:169] op_sel_hi:[1,0]
	v_pk_mul_f32 v[36:37], v[36:37], v[168:169] op_sel_hi:[1,0]
	v_pk_mul_f32 v[34:35], v[34:35], v[168:169] op_sel_hi:[1,0]
	v_pk_mul_f32 v[32:33], v[32:33], v[168:169] op_sel_hi:[1,0]
	s_waitcnt lgkmcnt(1)
	v_pk_mul_f32 v[30:31], v[30:31], v[172:173] op_sel_hi:[1,0]
	v_pk_mul_f32 v[28:29], v[28:29], v[172:173] op_sel_hi:[1,0]
	v_pk_mul_f32 v[26:27], v[26:27], v[172:173] op_sel_hi:[1,0]
	v_pk_mul_f32 v[24:25], v[24:25], v[172:173] op_sel_hi:[1,0]
	v_pk_mul_f32 v[22:23], v[22:23], v[172:173] op_sel_hi:[1,0]
	v_pk_mul_f32 v[20:21], v[20:21], v[172:173] op_sel_hi:[1,0]
	v_pk_mul_f32 v[18:19], v[18:19], v[172:173] op_sel_hi:[1,0]
	v_pk_mul_f32 v[16:17], v[16:17], v[172:173] op_sel_hi:[1,0]
	s_waitcnt lgkmcnt(0)
	v_pk_mul_f32 v[8:9], v[8:9], v[170:171] op_sel_hi:[1,0]
	v_pk_mul_f32 v[10:11], v[10:11], v[170:171] op_sel_hi:[1,0]
	s_andn2_b64 vcc, exec, s[8:9]
	v_pk_mul_f32 v[12:13], v[12:13], v[170:171] op_sel_hi:[1,0]
	v_pk_mul_f32 v[14:15], v[14:15], v[170:171] op_sel_hi:[1,0]
	s_mov_b64 s[8:9], -1
	s_waitcnt vmcnt(1)
	v_pk_mul_f32 v[6:7], v[6:7], v[126:127]
	v_pk_mul_f32 v[4:5], v[4:5], v[124:125]
	s_waitcnt vmcnt(0)
	v_pk_mul_f32 v[2:3], v[2:3], v[122:123]
	v_pk_mul_f32 v[0:1], v[0:1], v[120:121]
	global_store_dwordx4 v[146:147], v[4:7], off nt
	global_store_dwordx4 v[146:147], v[0:3], off offset:16 nt
	global_load_dwordx4 v[0:3], v[148:149], off offset:512
	s_nop 0
	global_load_dwordx4 v[4:7], v[148:149], off offset:528
	s_waitcnt vmcnt(1)
	v_pk_mul_f32 v[2:3], v[118:119], v[2:3]
	v_pk_mul_f32 v[0:1], v[116:117], v[0:1]
	s_waitcnt vmcnt(0)
	v_pk_mul_f32 v[6:7], v[114:115], v[6:7]
	v_pk_mul_f32 v[4:5], v[112:113], v[4:5]
	global_store_dwordx4 v[146:147], v[0:3], off offset:512 nt
	global_store_dwordx4 v[146:147], v[4:7], off offset:528 nt
	global_load_dwordx4 v[0:3], v[148:149], off
	s_nop 0
	global_load_dwordx4 v[4:7], v[148:149], off offset:16
	v_add_u32_e32 v112, s39, v167
	v_ashrrev_i32_e32 v113, 31, v112
	v_lshlrev_b64 v[112:113], 13, v[112:113]
	v_lshl_add_u64 v[112:113], s[12:13], 0, v[112:113]
	v_lshl_add_u64 v[112:113], v[112:113], 0, v[158:159]
	s_waitcnt vmcnt(1)
;     __device__ __forceinline__ void operator()(f32x4 (&acc)[2][2][4][2], const Unit& u, int wr, int wc, int fr, int fq) const {
;     ...
;             for (int m = 0; m < 4; ++m) { const int rl = ai * HALF + wr * 64 + m * 16 + fr; const float rstd = R[rl]; float* orow = out + (size_t)(u.pm * BM + rl) * D + col0;
; #pragma unroll
;                 for (int bj = 0; bj < 2; ++bj) { const f32x4 g0 = *(const f32x4*)(gain + col0 + bj * HALF), g1 = *(const f32x4*)(gain + col0 + bj * HALF + 4);
;                     *(f32x4*)(orow + bj * HALF) = acc[ai][bj][m][0] * rstd * g0; *(f32x4*)(orow + bj * HALF + 4) = acc[ai][bj][m][1] * rstd * g1; } }
	v_pk_mul_f32 v[2:3], v[2:3], v[110:111]
	v_pk_mul_f32 v[0:1], v[0:1], v[108:109]
	s_waitcnt vmcnt(0)
	v_pk_mul_f32 v[6:7], v[6:7], v[106:107]
	v_pk_mul_f32 v[4:5], v[4:5], v[104:105]
	global_store_dwordx4 v[112:113], v[0:3], off nt
	global_store_dwordx4 v[112:113], v[4:7], off offset:16 nt
	global_load_dwordx4 v[0:3], v[148:149], off offset:512
	s_nop 0
	global_load_dwordx4 v[4:7], v[148:149], off offset:528
	s_waitcnt vmcnt(1)
	v_pk_mul_f32 v[2:3], v[102:103], v[2:3]
	v_pk_mul_f32 v[0:1], v[100:101], v[0:1]
	s_waitcnt vmcnt(0)
	v_pk_mul_f32 v[6:7], v[98:99], v[6:7]
	v_pk_mul_f32 v[4:5], v[96:97], v[4:5]
	global_store_dwordx4 v[112:113], v[0:3], off offset:512 nt
	global_store_dwordx4 v[112:113], v[4:7], off offset:528 nt
	global_load_dwordx4 v[0:3], v[148:149], off
	s_nop 0
	global_load_dwordx4 v[4:7], v[148:149], off offset:16
	v_add_u32_e32 v96, s39, v169
	v_ashrrev_i32_e32 v97, 31, v96
	v_lshlrev_b64 v[96:97], 13, v[96:97]
	v_lshl_add_u64 v[96:97], s[12:13], 0, v[96:97]
	v_lshl_add_u64 v[96:97], v[96:97], 0, v[158:159]
	s_waitcnt vmcnt(1)
	v_pk_mul_f32 v[2:3], v[2:3], v[94:95]
	v_pk_mul_f32 v[0:1], v[0:1], v[92:93]
	s_waitcnt vmcnt(0)
	v_pk_mul_f32 v[6:7], v[6:7], v[90:91]
	v_pk_mul_f32 v[4:5], v[4:5], v[88:89]
	global_store_dwordx4 v[96:97], v[0:3], off nt
	global_store_dwordx4 v[96:97], v[4:7], off offset:16 nt
	global_load_dwordx4 v[0:3], v[148:149], off offset:512
	s_nop 0
	global_load_dwordx4 v[4:7], v[148:149], off offset:528
	s_waitcnt vmcnt(1)
	v_pk_mul_f32 v[2:3], v[86:87], v[2:3]
	v_pk_mul_f32 v[0:1], v[84:85], v[0:1]
	s_waitcnt vmcnt(0)
	v_pk_mul_f32 v[6:7], v[82:83], v[6:7]
	v_pk_mul_f32 v[4:5], v[80:81], v[4:5]
	global_store_dwordx4 v[96:97], v[0:3], off offset:512 nt
	global_store_dwordx4 v[96:97], v[4:7], off offset:528 nt
	global_load_dwordx4 v[0:3], v[148:149], off
	s_nop 0
	global_load_dwordx4 v[4:7], v[148:149], off offset:16
	v_add_u32_e32 v80, s39, v171
	v_ashrrev_i32_e32 v81, 31, v80
	v_lshlrev_b64 v[80:81], 13, v[80:81]
	v_lshl_add_u64 v[80:81], s[12:13], 0, v[80:81]
	v_lshl_add_u64 v[80:81], v[80:81], 0, v[158:159]
	s_waitcnt vmcnt(1)
	v_pk_mul_f32 v[2:3], v[2:3], v[78:79]
	v_pk_mul_f32 v[0:1], v[0:1], v[76:77]
	s_waitcnt vmcnt(0)
	v_pk_mul_f32 v[6:7], v[6:7], v[74:75]
	v_pk_mul_f32 v[4:5], v[4:5], v[72:73]
	global_store_dwordx4 v[80:81], v[0:3], off nt
	global_store_dwordx4 v[80:81], v[4:7], off offset:16 nt
	global_load_dwordx4 v[0:3], v[148:149], off offset:512
	s_nop 0
	global_load_dwordx4 v[4:7], v[148:149], off offset:528
	s_waitcnt vmcnt(1)
	v_pk_mul_f32 v[2:3], v[70:71], v[2:3]
	v_pk_mul_f32 v[0:1], v[68:69], v[0:1]
	s_waitcnt vmcnt(0)
	v_pk_mul_f32 v[6:7], v[66:67], v[6:7]
	v_pk_mul_f32 v[4:5], v[64:65], v[4:5]
	global_store_dwordx4 v[80:81], v[0:3], off offset:512 nt
	global_store_dwordx4 v[80:81], v[4:7], off offset:528 nt
	global_load_dwordx4 v[0:3], v[148:149], off
	s_nop 0
	global_load_dwordx4 v[4:7], v[148:149], off offset:16
	v_add_u32_e32 v64, s39, v173
	v_ashrrev_i32_e32 v65, 31, v64
	v_lshlrev_b64 v[64:65], 13, v[64:65]
	v_lshl_add_u64 v[64:65], s[12:13], 0, v[64:65]
	v_lshl_add_u64 v[64:65], v[64:65], 0, v[158:159]
	s_waitcnt vmcnt(1)
	v_pk_mul_f32 v[2:3], v[2:3], v[62:63]
	v_pk_mul_f32 v[0:1], v[0:1], v[60:61]
	s_waitcnt vmcnt(0)
	v_pk_mul_f32 v[6:7], v[6:7], v[58:59]
	v_pk_mul_f32 v[4:5], v[4:5], v[56:57]
	global_store_dwordx4 v[64:65], v[0:3], off nt
	global_store_dwordx4 v[64:65], v[4:7], off offset:16 nt
	global_load_dwordx4 v[0:3], v[148:149], off offset:512
	s_nop 0
	global_load_dwordx4 v[4:7], v[148:149], off offset:528
	s_waitcnt vmcnt(1)
	v_pk_mul_f32 v[2:3], v[54:55], v[2:3]
	v_pk_mul_f32 v[0:1], v[52:53], v[0:1]
	s_waitcnt vmcnt(0)
;     __device__ __forceinline__ void operator()(f32x4 (&acc)[2][2][4][2], const Unit& u, int wr, int wc, int fr, int fq) const {
;     ...
;             for (int m = 0; m < 4; ++m) { const int rl = ai * HALF + wr * 64 + m * 16 + fr; const float rstd = R[rl]; float* orow = out + (size_t)(u.pm * BM + rl) * D + col0;
; #pragma unroll
;                 for (int bj = 0; bj < 2; ++bj) { const f32x4 g0 = *(const f32x4*)(gain + col0 + bj * HALF), g1 = *(const f32x4*)(gain + col0 + bj * HALF + 4);
;                     *(f32x4*)(orow + bj * HALF) = acc[ai][bj][m][0] * rstd * g0; *(f32x4*)(orow + bj * HALF + 4) = acc[ai][bj][m][1] * rstd * g1; } }
	v_pk_mul_f32 v[6:7], v[50:51], v[6:7]
	v_pk_mul_f32 v[4:5], v[48:49], v[4:5]
	global_store_dwordx4 v[64:65], v[0:3], off offset:512 nt
	global_store_dwordx4 v[64:65], v[4:7], off offset:528 nt
	global_load_dwordx4 v[0:3], v[148:149], off
	s_nop 0
	global_load_dwordx4 v[4:7], v[148:149], off offset:16
	v_add_u32_e32 v48, s39, v174
	v_ashrrev_i32_e32 v49, 31, v48
	v_lshlrev_b64 v[48:49], 13, v[48:49]
	v_lshl_add_u64 v[48:49], s[12:13], 0, v[48:49]
	v_lshl_add_u64 v[48:49], v[48:49], 0, v[158:159]
	s_waitcnt vmcnt(1)
	v_pk_mul_f32 v[2:3], v[2:3], v[46:47]
	v_pk_mul_f32 v[0:1], v[0:1], v[44:45]
	s_waitcnt vmcnt(0)
	v_pk_mul_f32 v[6:7], v[6:7], v[42:43]
	v_pk_mul_f32 v[4:5], v[4:5], v[40:41]
	global_store_dwordx4 v[48:49], v[0:3], off nt
	global_store_dwordx4 v[48:49], v[4:7], off offset:16 nt
	global_load_dwordx4 v[0:3], v[148:149], off offset:512
	s_nop 0
	global_load_dwordx4 v[4:7], v[148:149], off offset:528
	s_waitcnt vmcnt(1)
	v_pk_mul_f32 v[2:3], v[38:39], v[2:3]
	v_pk_mul_f32 v[0:1], v[36:37], v[0:1]
	s_waitcnt vmcnt(0)
	v_pk_mul_f32 v[6:7], v[34:35], v[6:7]
	v_pk_mul_f32 v[4:5], v[32:33], v[4:5]
	global_store_dwordx4 v[48:49], v[0:3], off offset:512 nt
	global_store_dwordx4 v[48:49], v[4:7], off offset:528 nt
	global_load_dwordx4 v[0:3], v[148:149], off
	s_nop 0
	global_load_dwordx4 v[4:7], v[148:149], off offset:16
	v_add_u32_e32 v32, s39, v175
	v_ashrrev_i32_e32 v33, 31, v32
	v_lshlrev_b64 v[32:33], 13, v[32:33]
	v_lshl_add_u64 v[32:33], s[12:13], 0, v[32:33]
	v_lshl_add_u64 v[32:33], v[32:33], 0, v[158:159]
	s_waitcnt vmcnt(1)
	v_pk_mul_f32 v[2:3], v[2:3], v[30:31]
	v_pk_mul_f32 v[0:1], v[0:1], v[28:29]
	s_waitcnt vmcnt(0)
	v_pk_mul_f32 v[6:7], v[6:7], v[26:27]
	v_pk_mul_f32 v[4:5], v[4:5], v[24:25]
	global_store_dwordx4 v[32:33], v[0:3], off nt
	global_store_dwordx4 v[32:33], v[4:7], off offset:16 nt
	global_load_dwordx4 v[0:3], v[148:149], off offset:512
	s_nop 0
	global_load_dwordx4 v[4:7], v[148:149], off offset:528
	v_pk_mul_f32 v[24:25], v[152:153], v[170:171] op_sel_hi:[1,0]
	s_waitcnt vmcnt(1)
	v_pk_mul_f32 v[2:3], v[22:23], v[2:3]
	v_pk_mul_f32 v[0:1], v[20:21], v[0:1]
	s_waitcnt vmcnt(0)
	v_pk_mul_f32 v[6:7], v[18:19], v[6:7]
	v_pk_mul_f32 v[4:5], v[16:17], v[4:5]
	global_store_dwordx4 v[32:33], v[0:3], off offset:512 nt
	global_store_dwordx4 v[32:33], v[4:7], off offset:528 nt
	global_load_dwordx4 v[0:3], v[148:149], off
	s_nop 0
	global_load_dwordx4 v[4:7], v[148:149], off offset:16
	v_add_u32_e32 v16, s39, v176
	v_ashrrev_i32_e32 v17, 31, v16
	v_lshlrev_b64 v[16:17], 13, v[16:17]
	v_lshl_add_u64 v[16:17], s[12:13], 0, v[16:17]
	v_pk_mul_f32 v[18:19], v[154:155], v[170:171] op_sel_hi:[1,0]
	v_pk_mul_f32 v[20:21], v[156:157], v[170:171] op_sel_hi:[1,0]
	v_lshl_add_u64 v[16:17], v[16:17], 0, v[158:159]
	v_pk_mul_f32 v[22:23], v[150:151], v[170:171] op_sel_hi:[1,0]
	s_waitcnt vmcnt(1)
	v_pk_mul_f32 v[2:3], v[2:3], v[18:19]
	v_pk_mul_f32 v[0:1], v[0:1], v[20:21]
	s_waitcnt vmcnt(0)
	v_pk_mul_f32 v[6:7], v[6:7], v[22:23]
	v_pk_mul_f32 v[4:5], v[4:5], v[24:25]
	global_store_dwordx4 v[16:17], v[0:3], off nt
	global_store_dwordx4 v[16:17], v[4:7], off offset:16 nt
	global_load_dwordx4 v[0:3], v[148:149], off offset:512
	s_nop 0
	global_load_dwordx4 v[4:7], v[148:149], off offset:528
	s_waitcnt vmcnt(1)
	v_pk_mul_f32 v[2:3], v[8:9], v[2:3]
	v_pk_mul_f32 v[0:1], v[10:11], v[0:1]
	s_waitcnt vmcnt(0)
	v_pk_mul_f32 v[6:7], v[12:13], v[6:7]
	v_pk_mul_f32 v[4:5], v[14:15], v[4:5]
	global_store_dwordx4 v[16:17], v[0:3], off offset:512 nt
	global_store_dwordx4 v[16:17], v[4:7], off offset:528 nt
	s_cbranch_vccnz .LBB0_1270
	s_andn2_b64 vcc, exec, s[26:27]
	s_cbranch_vccnz .LBB0_1269
	s_barrier
	s_branch .LBB0_1269
